# k20b: k20 + FFN-out loop back-edge counter block hoisted into the preceding load phase
# speedup vs baseline: 1.0004x; 1.0004x over previous
; #define PG8_STAGE(bufoff, gbase, voff) do { _Pragma("unroll") for (int _i = 0; _i < 2; ++_i) \
;         __builtin_amdgcn_global_load_lds((const unsigned*)((const char*)(gbase) + (voff)[_i]), (LAS unsigned*)(lds + (bufoff) + ldsw + _i * 8192), 16, 0, 0); } while (0)
; #define PG8_LDA(dst, b, h) do { _Pragma("unroll") for (int m = 0; m < 4; ++m) _Pragma("unroll") for (int k = 0; k < 2; ++k) dst[m][k] = *(const LAS bf16x8*)(lds + PG8_SA(b, h) + aoff + m * 2048 + k * 1024); } while (0)
; #define PG8_LDB(dst, b, h) do { _Pragma("unroll") for (int n = 0; n < 2; ++n) _Pragma("unroll") for (int k = 0; k < 2; ++k) dst[n][k] = *(const LAS bf16x8*)(lds + PG8_SB(b, h) + boff + n * 2048 + k * 1024); } while (0)
; #define PG8_MMA(ai, bj, At, Bt) do { __builtin_amdgcn_s_setprio(1); _Pragma("unroll") for (int m = 0; m < 4; ++m) _Pragma("unroll") for (int n = 0; n < 2; ++n) _Pragma("unroll") for (int k = 0; k < 2; ++k) \
;         acc[ai][bj][m][n] = __builtin_amdgcn_mfma_f32_16x16x32_bf16(Bt[n][k], At[m][k], acc[ai][bj][m][n], 0, 0, 0); __builtin_amdgcn_s_setprio(0); } while (0)
; #define PG8_WAIT_L(n) asm volatile("s_waitcnt lgkmcnt(" #n ")" ::: "memory")
; #define PG8_BAR __builtin_amdgcn_s_barrier()
; #define PG8_SCHED __builtin_amdgcn_sched_barrier(0)
; template <class Epi>
; __device__ __forceinline__ void gemm_phase(LAS unsigned char* lds, const Gemm g, const Epi& E) {
;     ...
;             PG8_LDB(B0, 0, 0); PG8_SCHED; PG8_LDA(At, 0, 0); PG8_STAGE(PG8_SA(1, 1), a1 + hstepA, voffA);
;             PG8_WAIT_L(8); PG8_BAR; PG8_WAIT_L(0); PG8_MMA(0, 0, At, B0); PG8_BAR; PG8_SCHED;
;             PG8_LDB(B1, 0, 1); PG8_STAGE(PG8_SB(0, 0), b2, voffB);
;             PG8_BAR; PG8_WAIT_L(0); PG8_MMA(0, 1, At, B1); PG8_BAR;
;             PG8_LDA(At, 0, 1); PG8_STAGE(PG8_SA(0, 0), a2, voffA);
;             PG8_BAR; PG8_WAIT_L(0); PG8_MMA(1, 0, At, B0); PG8_BAR; PG8_SCHED;
.LBB0_547:
	s_add_u32 s10, s8, 0x100
	s_addc_u32 s11, s9, 0
	s_add_i32 s26, 0, 0x10000
	v_add_u32_e32 v142, s26, v157
	ds_read_b128 v[130:133], v142
	ds_read_b128 v[134:137], v142 offset:1024
	ds_read_b128 v[138:141], v142 offset:2048
	ds_read_b128 v[142:145], v142 offset:3072
	s_cmp_eq_u32 s67, 40
	s_cselect_b32 s15, s5, s11
	s_cselect_b32 s14, s4, s10
	s_cselect_b32 s13, s7, s66
	s_cselect_b32 s12, s6, s65
	v_lshl_add_u64 v[154:155], s[8:9], 0, v[150:151]
	s_add_i32 m0, s29, 0xc000
	ds_read_b128 v[160:163], v158
	ds_read_b128 v[164:167], v158 offset:1024
	ds_read_b128 v[168:171], v158 offset:2048
	ds_read_b128 v[172:175], v158 offset:3072
	ds_read_b128 v[180:183], v158 offset:4096
	ds_read_b128 v[184:187], v158 offset:5120
	ds_read_b128 v[188:191], v158 offset:6144
	ds_read_b128 v[192:195], v158 offset:7168
	global_load_lds_dwordx4 v[154:155], off
	v_lshl_add_u64 v[154:155], s[8:9], 0, v[152:153]
	s_add_i32 m0, s29, 0xe000
	s_nop 0
	global_load_lds_dwordx4 v[154:155], off
	s_waitcnt lgkmcnt(8)
	s_barrier
	s_waitcnt lgkmcnt(0)
	v_mfma_f32_16x16x32_bf16 v[126:129], v[130:133], v[160:163], v[126:129]
	v_mfma_f32_16x16x32_bf16 v[122:125], v[138:141], v[160:163], v[122:125]
	v_mfma_f32_16x16x32_bf16 v[118:121], v[130:133], v[168:171], v[118:121]
	v_mfma_f32_16x16x32_bf16 v[110:113], v[138:141], v[168:171], v[110:113]
	v_mfma_f32_16x16x32_bf16 v[102:105], v[130:133], v[180:183], v[102:105]
	v_mfma_f32_16x16x32_bf16 v[94:97], v[138:141], v[180:183], v[94:97]
	v_mfma_f32_16x16x32_bf16 v[86:89], v[130:133], v[188:191], v[86:89]
	v_mfma_f32_16x16x32_bf16 v[78:81], v[138:141], v[188:191], v[78:81]
	v_mfma_f32_16x16x32_bf16 v[126:129], v[134:137], v[164:167], v[126:129]
	v_mfma_f32_16x16x32_bf16 v[122:125], v[142:145], v[164:167], v[122:125]
	v_mfma_f32_16x16x32_bf16 v[118:121], v[134:137], v[172:175], v[118:121]
	v_mfma_f32_16x16x32_bf16 v[110:113], v[142:145], v[172:175], v[110:113]
	v_mfma_f32_16x16x32_bf16 v[102:105], v[134:137], v[184:187], v[102:105]
	v_mfma_f32_16x16x32_bf16 v[94:97], v[142:145], v[184:187], v[94:97]
	v_mfma_f32_16x16x32_bf16 v[86:89], v[134:137], v[192:195], v[86:89]
	v_mfma_f32_16x16x32_bf16 v[78:81], v[142:145], v[192:195], v[78:81]
	s_barrier
	s_add_i32 s27, 0, 0x14000
	v_add_u32_e32 v154, s27, v157
	s_add_i32 s8, s26, s18
	ds_read_b128 v[196:199], v154
	ds_read_b128 v[200:203], v154 offset:1024
	ds_read_b128 v[204:207], v154 offset:2048
	ds_read_b128 v[226:229], v154 offset:3072
	v_lshl_add_u64 v[154:155], s[12:13], 0, v[148:149]
	s_mov_b32 m0, s8
	v_lshl_add_u64 v[176:177], s[12:13], 0, v[146:147]
	global_load_lds_dwordx4 v[154:155], off
	s_add_i32 m0, s8, 0x2000
	s_nop 0
	global_load_lds_dwordx4 v[176:177], off
	s_nop 1
	s_mov_b32 m0, s29
	v_lshl_add_u64 v[208:209], s[14:15], 0, v[148:149]
	s_barrier
	s_waitcnt lgkmcnt(0)
	v_mfma_f32_16x16x32_bf16 v[114:117], v[196:199], v[160:163], v[114:117]
	v_mfma_f32_16x16x32_bf16 v[106:109], v[204:207], v[160:163], v[106:109]
	v_mfma_f32_16x16x32_bf16 v[98:101], v[196:199], v[168:171], v[98:101]
	v_mfma_f32_16x16x32_bf16 v[90:93], v[204:207], v[168:171], v[90:93]
	v_mfma_f32_16x16x32_bf16 v[82:85], v[196:199], v[180:183], v[82:85]
	v_mfma_f32_16x16x32_bf16 v[74:77], v[204:207], v[180:183], v[74:77]
	v_mfma_f32_16x16x32_bf16 v[70:73], v[196:199], v[188:191], v[70:73]
	v_mfma_f32_16x16x32_bf16 v[66:69], v[204:207], v[188:191], v[66:69]
	v_mfma_f32_16x16x32_bf16 v[114:117], v[200:203], v[164:167], v[114:117]
	v_mfma_f32_16x16x32_bf16 v[106:109], v[226:229], v[164:167], v[106:109]
	v_mfma_f32_16x16x32_bf16 v[98:101], v[200:203], v[172:175], v[98:101]
	v_mfma_f32_16x16x32_bf16 v[90:93], v[226:229], v[172:175], v[90:93]
	v_mfma_f32_16x16x32_bf16 v[82:85], v[200:203], v[184:187], v[82:85]
	v_mfma_f32_16x16x32_bf16 v[74:77], v[226:229], v[184:187], v[74:77]
	v_mfma_f32_16x16x32_bf16 v[70:73], v[200:203], v[192:195], v[70:73]
	v_mfma_f32_16x16x32_bf16 v[66:69], v[226:229], v[192:195], v[66:69]
	s_barrier
	ds_read_b128 v[160:163], v158 offset:16384
	ds_read_b128 v[164:167], v158 offset:17408
	ds_read_b128 v[168:171], v158 offset:18432
	ds_read_b128 v[172:175], v158 offset:19456
	ds_read_b128 v[180:183], v158 offset:20480
	ds_read_b128 v[184:187], v158 offset:21504
	ds_read_b128 v[188:191], v158 offset:22528
	ds_read_b128 v[192:195], v158 offset:23552
	global_load_lds_dwordx4 v[208:209], off
	v_lshl_add_u64 v[230:231], s[14:15], 0, v[146:147]
	s_mov_b32 m0, s30
	s_nop 0
	global_load_lds_dwordx4 v[230:231], off
	s_barrier
	s_waitcnt lgkmcnt(0)
	v_mfma_f32_16x16x32_bf16 v[62:65], v[130:133], v[160:163], v[62:65]
	v_mfma_f32_16x16x32_bf16 v[58:61], v[138:141], v[160:163], v[58:61]
	v_mfma_f32_16x16x32_bf16 v[54:57], v[130:133], v[168:171], v[54:57]
	v_mfma_f32_16x16x32_bf16 v[46:49], v[138:141], v[168:171], v[46:49]
	v_mfma_f32_16x16x32_bf16 v[38:41], v[130:133], v[180:183], v[38:41]
	v_mfma_f32_16x16x32_bf16 v[30:33], v[138:141], v[180:183], v[30:33]
	v_mfma_f32_16x16x32_bf16 v[22:25], v[130:133], v[188:191], v[22:25]
	v_mfma_f32_16x16x32_bf16 v[14:17], v[138:141], v[188:191], v[14:17]
	v_mfma_f32_16x16x32_bf16 v[62:65], v[134:137], v[164:167], v[62:65]
	v_mfma_f32_16x16x32_bf16 v[58:61], v[142:145], v[164:167], v[58:61]
	v_mfma_f32_16x16x32_bf16 v[54:57], v[134:137], v[172:175], v[54:57]
	v_mfma_f32_16x16x32_bf16 v[46:49], v[142:145], v[172:175], v[46:49]
	v_mfma_f32_16x16x32_bf16 v[38:41], v[134:137], v[184:187], v[38:41]
	v_mfma_f32_16x16x32_bf16 v[30:33], v[142:145], v[184:187], v[30:33]
	v_mfma_f32_16x16x32_bf16 v[22:25], v[134:137], v[192:195], v[22:25]
	v_mfma_f32_16x16x32_bf16 v[14:17], v[142:145], v[192:195], v[14:17]
	s_barrier
; #define PG8_STAGE(bufoff, gbase, voff) do { _Pragma("unroll") for (int _i = 0; _i < 2; ++_i) \
;         __builtin_amdgcn_global_load_lds((const unsigned*)((const char*)(gbase) + (voff)[_i]), (LAS unsigned*)(lds + (bufoff) + ldsw + _i * 8192), 16, 0, 0); } while (0)
; #define PG8_LDA(dst, b, h) do { _Pragma("unroll") for (int m = 0; m < 4; ++m) _Pragma("unroll") for (int k = 0; k < 2; ++k) dst[m][k] = *(const LAS bf16x8*)(lds + PG8_SA(b, h) + aoff + m * 2048 + k * 1024); } while (0)
; #define PG8_LDB(dst, b, h) do { _Pragma("unroll") for (int n = 0; n < 2; ++n) _Pragma("unroll") for (int k = 0; k < 2; ++k) dst[n][k] = *(const LAS bf16x8*)(lds + PG8_SB(b, h) + boff + n * 2048 + k * 1024); } while (0)
; #define PG8_MMA(ai, bj, At, Bt) do { __builtin_amdgcn_s_setprio(1); _Pragma("unroll") for (int m = 0; m < 4; ++m) _Pragma("unroll") for (int n = 0; n < 2; ++n) _Pragma("unroll") for (int k = 0; k < 2; ++k) \
;         acc[ai][bj][m][n] = __builtin_amdgcn_mfma_f32_16x16x32_bf16(Bt[n][k], At[m][k], acc[ai][bj][m][n], 0, 0, 0); __builtin_amdgcn_s_setprio(0); } while (0)
; #define PG8_WAIT_V(n) asm volatile("s_waitcnt vmcnt(" #n ")" ::: "memory")
; #define PG8_WAIT_L(n) asm volatile("s_waitcnt lgkmcnt(" #n ")" ::: "memory")
; #define PG8_BAR __builtin_amdgcn_s_barrier()
; #define PG8_SCHED __builtin_amdgcn_sched_barrier(0)
; template <class Epi>
; __device__ __forceinline__ void gemm_phase(LAS unsigned char* lds, const Gemm g, const Epi& E) {
;     ...
;             PG8_STAGE(PG8_SB(0, 1), b2 + hstepB, voffB);
;             PG8_WAIT_V(6); PG8_BAR; PG8_MMA(1, 1, At, B1); PG8_BAR;
;             PG8_LDB(B0, 1, 0); PG8_SCHED; PG8_LDA(At, 1, 0); PG8_STAGE(PG8_SA(0, 1), a2 + hstepA, voffA);
;             PG8_WAIT_L(8); PG8_BAR; PG8_WAIT_L(0); PG8_MMA(0, 0, At, B0); PG8_BAR; PG8_SCHED;
;             PG8_LDB(B1, 1, 1); PG8_STAGE(PG8_SB(1, 0), b3, voffB);
;             PG8_BAR; PG8_WAIT_L(0); PG8_MMA(0, 1, At, B1); PG8_BAR;
;             PG8_LDA(At, 1, 1); PG8_STAGE(PG8_SA(1, 0), a3, voffA);
	s_add_u32 s8, s12, 0xb0000
	s_addc_u32 s9, s13, 0
	s_add_i32 s26, s27, s18
	v_lshl_add_u64 v[130:131], s[8:9], 0, v[148:149]
	s_mov_b32 m0, s26
	s_nop 0
	global_load_lds_dwordx4 v[130:131], off
	v_lshl_add_u64 v[130:131], s[8:9], 0, v[146:147]
	s_add_i32 m0, s26, 0x2000
	s_nop 0
	global_load_lds_dwordx4 v[130:131], off
	s_add_i32 s26, 0, 0x18000
	v_add_u32_e32 v142, s26, v157
	s_waitcnt vmcnt(6)
	s_barrier
	v_mfma_f32_16x16x32_bf16 v[50:53], v[196:199], v[160:163], v[50:53]
	v_mfma_f32_16x16x32_bf16 v[42:45], v[204:207], v[160:163], v[42:45]
	v_mfma_f32_16x16x32_bf16 v[34:37], v[196:199], v[168:171], v[34:37]
	v_mfma_f32_16x16x32_bf16 v[26:29], v[204:207], v[168:171], v[26:29]
	v_mfma_f32_16x16x32_bf16 v[18:21], v[196:199], v[180:183], v[18:21]
	v_mfma_f32_16x16x32_bf16 v[10:13], v[204:207], v[180:183], v[10:13]
	v_mfma_f32_16x16x32_bf16 v[6:9], v[196:199], v[188:191], v[6:9]
	v_mfma_f32_16x16x32_bf16 v[2:5], v[204:207], v[188:191], v[2:5]
	v_mfma_f32_16x16x32_bf16 v[50:53], v[200:203], v[164:167], v[50:53]
	v_mfma_f32_16x16x32_bf16 v[42:45], v[226:229], v[164:167], v[42:45]
	v_mfma_f32_16x16x32_bf16 v[34:37], v[200:203], v[172:175], v[34:37]
	v_mfma_f32_16x16x32_bf16 v[26:29], v[226:229], v[172:175], v[26:29]
	v_mfma_f32_16x16x32_bf16 v[18:21], v[200:203], v[184:187], v[18:21]
	v_mfma_f32_16x16x32_bf16 v[10:13], v[226:229], v[184:187], v[10:13]
	v_mfma_f32_16x16x32_bf16 v[6:9], v[200:203], v[192:195], v[6:9]
	v_mfma_f32_16x16x32_bf16 v[2:5], v[226:229], v[192:195], v[2:5]
	s_barrier
	ds_read_b128 v[130:133], v142
	ds_read_b128 v[134:137], v142 offset:1024
	ds_read_b128 v[138:141], v142 offset:2048
	ds_read_b128 v[142:145], v142 offset:3072
	s_add_u32 s8, s14, 0xb0000
	s_addc_u32 s9, s15, 0
	s_mov_b32 m0, s31
	v_lshl_add_u64 v[196:197], s[8:9], 0, v[148:149]
	ds_read_b128 v[160:163], v158 offset:32768
	ds_read_b128 v[164:167], v158 offset:33792
	ds_read_b128 v[168:171], v158 offset:34816
	ds_read_b128 v[172:175], v158 offset:35840
	ds_read_b128 v[180:183], v158 offset:36864
	ds_read_b128 v[184:187], v158 offset:37888
	ds_read_b128 v[188:191], v158 offset:38912
	ds_read_b128 v[192:195], v158 offset:39936
	global_load_lds_dwordx4 v[196:197], off
	v_lshl_add_u64 v[196:197], s[8:9], 0, v[146:147]
	s_mov_b32 m0, s36
	s_nop 0
	global_load_lds_dwordx4 v[196:197], off
	s_waitcnt lgkmcnt(8)
	s_barrier
	s_waitcnt lgkmcnt(0)
	v_mfma_f32_16x16x32_bf16 v[126:129], v[130:133], v[160:163], v[126:129]
	v_mfma_f32_16x16x32_bf16 v[122:125], v[138:141], v[160:163], v[122:125]
	v_mfma_f32_16x16x32_bf16 v[118:121], v[130:133], v[168:171], v[118:121]
	v_mfma_f32_16x16x32_bf16 v[110:113], v[138:141], v[168:171], v[110:113]
	v_mfma_f32_16x16x32_bf16 v[102:105], v[130:133], v[180:183], v[102:105]
	v_mfma_f32_16x16x32_bf16 v[94:97], v[138:141], v[180:183], v[94:97]
	v_mfma_f32_16x16x32_bf16 v[86:89], v[130:133], v[188:191], v[86:89]
	v_mfma_f32_16x16x32_bf16 v[78:81], v[138:141], v[188:191], v[78:81]
	v_mfma_f32_16x16x32_bf16 v[126:129], v[134:137], v[164:167], v[126:129]
	v_mfma_f32_16x16x32_bf16 v[122:125], v[142:145], v[164:167], v[122:125]
	v_mfma_f32_16x16x32_bf16 v[118:121], v[134:137], v[172:175], v[118:121]
	v_mfma_f32_16x16x32_bf16 v[110:113], v[142:145], v[172:175], v[110:113]
	v_mfma_f32_16x16x32_bf16 v[102:105], v[134:137], v[184:187], v[102:105]
	v_mfma_f32_16x16x32_bf16 v[94:97], v[142:145], v[184:187], v[94:97]
	v_mfma_f32_16x16x32_bf16 v[86:89], v[134:137], v[192:195], v[86:89]
	v_mfma_f32_16x16x32_bf16 v[78:81], v[142:145], v[192:195], v[78:81]
	s_barrier
	s_add_i32 s14, 0, 0x1c000
	s_add_i32 s8, s26, s18
	v_add_u32_e32 v159, s14, v157
	v_lshl_add_u64 v[154:155], v[154:155], 0, s[86:87]
	s_mov_b32 m0, s8
	ds_read_b128 v[196:199], v159
	ds_read_b128 v[200:203], v159 offset:1024
	ds_read_b128 v[204:207], v159 offset:2048
	ds_read_b128 v[226:229], v159 offset:3072
	global_load_lds_dwordx4 v[154:155], off
	v_lshl_add_u64 v[154:155], v[176:177], 0, s[86:87]
	s_add_i32 m0, s8, 0x2000
	s_nop 0
	global_load_lds_dwordx4 v[154:155], off
	s_nop 1
	s_mov_b32 m0, s52
	v_lshl_add_u64 v[154:155], v[208:209], 0, s[86:87]
	s_barrier
	s_waitcnt lgkmcnt(0)
	v_mfma_f32_16x16x32_bf16 v[114:117], v[196:199], v[160:163], v[114:117]
	v_mfma_f32_16x16x32_bf16 v[106:109], v[204:207], v[160:163], v[106:109]
	v_mfma_f32_16x16x32_bf16 v[98:101], v[196:199], v[168:171], v[98:101]
	v_mfma_f32_16x16x32_bf16 v[90:93], v[204:207], v[168:171], v[90:93]
	v_mfma_f32_16x16x32_bf16 v[82:85], v[196:199], v[180:183], v[82:85]
	v_mfma_f32_16x16x32_bf16 v[74:77], v[204:207], v[180:183], v[74:77]
	v_mfma_f32_16x16x32_bf16 v[70:73], v[196:199], v[188:191], v[70:73]
	v_mfma_f32_16x16x32_bf16 v[66:69], v[204:207], v[188:191], v[66:69]
	v_mfma_f32_16x16x32_bf16 v[114:117], v[200:203], v[164:167], v[114:117]
	v_mfma_f32_16x16x32_bf16 v[106:109], v[226:229], v[164:167], v[106:109]
	v_mfma_f32_16x16x32_bf16 v[98:101], v[200:203], v[172:175], v[98:101]
	v_mfma_f32_16x16x32_bf16 v[90:93], v[226:229], v[172:175], v[90:93]
	v_mfma_f32_16x16x32_bf16 v[82:85], v[200:203], v[184:187], v[82:85]
	v_mfma_f32_16x16x32_bf16 v[74:77], v[226:229], v[184:187], v[74:77]
	v_mfma_f32_16x16x32_bf16 v[70:73], v[200:203], v[192:195], v[70:73]
	v_mfma_f32_16x16x32_bf16 v[66:69], v[226:229], v[192:195], v[66:69]
	s_barrier
	ds_read_b128 v[160:163], v158 offset:49152
	ds_read_b128 v[164:167], v158 offset:50176
	ds_read_b128 v[168:171], v158 offset:51200
	ds_read_b128 v[172:175], v158 offset:52224
	ds_read_b128 v[180:183], v158 offset:53248
	ds_read_b128 v[184:187], v158 offset:54272
	ds_read_b128 v[188:191], v158 offset:55296
	ds_read_b128 v[192:195], v158 offset:56320
	global_load_lds_dwordx4 v[154:155], off
	v_lshl_add_u64 v[154:155], v[230:231], 0, s[86:87]
	s_mov_b32 m0, s53
	s_nop 0
	global_load_lds_dwordx4 v[154:155], off
	s_barrier
; #define PG8_STAGE(bufoff, gbase, voff) do { _Pragma("unroll") for (int _i = 0; _i < 2; ++_i) \
;         __builtin_amdgcn_global_load_lds((const unsigned*)((const char*)(gbase) + (voff)[_i]), (LAS unsigned*)(lds + (bufoff) + ldsw + _i * 8192), 16, 0, 0); } while (0)
; #define PG8_LDA(dst, b, h) do { _Pragma("unroll") for (int m = 0; m < 4; ++m) _Pragma("unroll") for (int k = 0; k < 2; ++k) dst[m][k] = *(const LAS bf16x8*)(lds + PG8_SA(b, h) + aoff + m * 2048 + k * 1024); } while (0)
; #define PG8_WAIT_V(n) asm volatile("s_waitcnt vmcnt(" #n ")" ::: "memory")
; #define PG8_WAIT_L(n) asm volatile("s_waitcnt lgkmcnt(" #n ")" ::: "memory")
; #define PG8_BAR __builtin_amdgcn_s_barrier()
; #define PG8_SCHED __builtin_amdgcn_sched_barrier(0)
; template <class Epi>
; __device__ __forceinline__ void gemm_phase(LAS unsigned char* lds, const Gemm g, const Epi& E) {
;     ...
;             PG8_BAR; PG8_WAIT_L(0); PG8_MMA(0, 1, At, B1); PG8_BAR;
;             PG8_LDA(At, 1, 1); PG8_STAGE(PG8_SA(1, 0), a3, voffA);
;             PG8_BAR; PG8_WAIT_L(0); PG8_MMA(1, 0, At, B0); PG8_BAR; PG8_SCHED;
;             PG8_STAGE(PG8_SB(1, 1), b3 + hstepB, voffB);
;             PG8_WAIT_V(6); PG8_BAR; PG8_MMA(1, 1, At, B1); PG8_BAR;
;     __device__ __forceinline__ void operator()(const AccT& acc, const Unit& u, int wr, int wc, int fr, int fq) const {
;     ...
;         const int gpm = mapA.src(u.pm);
;         const int mb = gpm < 32 ? 32 : (gpm - 32) >> 3;
;         const int row0 = gpm * 256 + wr * 64 + fr, col0 = u.pn * 256 + wc * 32 + 4 * fq;
;         const float* gp = modl + ((size_t)mb * 6 + gi) * 1024;
;         f32x4 gv[2][2];
; #pragma unroll
;         for (int bj = 0; bj < 2; ++bj)
; #pragma unroll
;             for (int n = 0; n < 2; ++n) { gv[bj][n] = *(const f32x4*)(gp + col0 + bj * 128 + n * 16); if (scale) gv[bj][n] = gv[bj][n] * *(const f32x4*)(scale + col0 + bj * 128 + n * 16); }
;         const float* sbase = (gpm < 32 ? Xc : Xl) + (size_t)row0 * 1024 + col0;
; #pragma unroll
;         for (int ai = 0; ai < 2; ++ai) {
;             f32x4 xo[4][2][2];
; #pragma unroll
;             for (int m = 0; m < 4; ++m)
; #pragma unroll
;                 for (int bj = 0; bj < 2; ++bj)
; #pragma unroll
;                     for (int n = 0; n < 2; ++n) xo[m][bj][n] = *(const f32x4*)(sbase + (size_t)(ai * 128 + m * 16) * 1024 + bj * 128 + n * 16);
	s_waitcnt lgkmcnt(0)
	v_mfma_f32_16x16x32_bf16 v[62:65], v[130:133], v[160:163], v[62:65]
	v_mfma_f32_16x16x32_bf16 v[58:61], v[138:141], v[160:163], v[58:61]
	v_mfma_f32_16x16x32_bf16 v[54:57], v[130:133], v[168:171], v[54:57]
	v_mfma_f32_16x16x32_bf16 v[46:49], v[138:141], v[168:171], v[46:49]
	v_mfma_f32_16x16x32_bf16 v[38:41], v[130:133], v[180:183], v[38:41]
	v_mfma_f32_16x16x32_bf16 v[30:33], v[138:141], v[180:183], v[30:33]
	v_mfma_f32_16x16x32_bf16 v[22:25], v[130:133], v[188:191], v[22:25]
	v_mfma_f32_16x16x32_bf16 v[14:17], v[138:141], v[188:191], v[14:17]
	v_mfma_f32_16x16x32_bf16 v[62:65], v[134:137], v[164:167], v[62:65]
	v_mfma_f32_16x16x32_bf16 v[58:61], v[142:145], v[164:167], v[58:61]
	v_mfma_f32_16x16x32_bf16 v[54:57], v[134:137], v[172:175], v[54:57]
	v_mfma_f32_16x16x32_bf16 v[46:49], v[142:145], v[172:175], v[46:49]
	v_mfma_f32_16x16x32_bf16 v[38:41], v[134:137], v[184:187], v[38:41]
	v_mfma_f32_16x16x32_bf16 v[30:33], v[142:145], v[184:187], v[30:33]
	v_mfma_f32_16x16x32_bf16 v[22:25], v[134:137], v[192:195], v[22:25]
	v_mfma_f32_16x16x32_bf16 v[14:17], v[142:145], v[192:195], v[14:17]
	s_barrier
	s_add_u32 s8, s12, 0xb0080
	s_addc_u32 s9, s13, 0
	s_add_i32 s12, s14, s18
	v_lshl_add_u64 v[130:131], s[8:9], 0, v[148:149]
	s_mov_b32 m0, s12
	s_nop 0
	global_load_lds_dwordx4 v[130:131], off
	v_lshl_add_u64 v[130:131], s[8:9], 0, v[146:147]
	s_add_i32 m0, s12, 0x2000
	s_nop 0
	global_load_lds_dwordx4 v[130:131], off
	s_add_i32 s67, s67, 2
	s_add_u32 s65, s65, 0x100
	s_addc_u32 s66, s66, 0
	s_cmp_gt_u32 s67, 41
	s_mov_b64 s[8:9], s[10:11]
	s_waitcnt vmcnt(6)
	s_barrier
	v_mfma_f32_16x16x32_bf16 v[50:53], v[196:199], v[160:163], v[50:53]
	v_mfma_f32_16x16x32_bf16 v[42:45], v[204:207], v[160:163], v[42:45]
	v_mfma_f32_16x16x32_bf16 v[34:37], v[196:199], v[168:171], v[34:37]
	v_mfma_f32_16x16x32_bf16 v[26:29], v[204:207], v[168:171], v[26:29]
	v_mfma_f32_16x16x32_bf16 v[18:21], v[196:199], v[180:183], v[18:21]
	v_mfma_f32_16x16x32_bf16 v[10:13], v[204:207], v[180:183], v[10:13]
	v_mfma_f32_16x16x32_bf16 v[6:9], v[196:199], v[188:191], v[6:9]
	v_mfma_f32_16x16x32_bf16 v[2:5], v[204:207], v[188:191], v[2:5]
	v_mfma_f32_16x16x32_bf16 v[50:53], v[200:203], v[164:167], v[50:53]
	v_mfma_f32_16x16x32_bf16 v[42:45], v[226:229], v[164:167], v[42:45]
	v_mfma_f32_16x16x32_bf16 v[34:37], v[200:203], v[172:175], v[34:37]
	v_mfma_f32_16x16x32_bf16 v[26:29], v[226:229], v[172:175], v[26:29]
	v_mfma_f32_16x16x32_bf16 v[18:21], v[200:203], v[184:187], v[18:21]
	v_mfma_f32_16x16x32_bf16 v[10:13], v[226:229], v[184:187], v[10:13]
	v_mfma_f32_16x16x32_bf16 v[6:9], v[200:203], v[192:195], v[6:9]
	v_mfma_f32_16x16x32_bf16 v[2:5], v[226:229], v[192:195], v[2:5]
	s_barrier
	s_cbranch_scc0 .LBB0_547
	v_readlane_b32 s8, v255, 27
	s_cmp_ge_i32 s64, s8
	s_cselect_b32 s8, s25, 0
	s_add_i32 s10, s64, s8
	s_sub_i32 s8, s10, 32
	s_lshl_b32 s9, s61, 8
	s_ashr_i32 s8, s8, 3
	s_or_b32 s9, s9, s50
	v_mov_b32_e32 v130, v1
	v_mov_b32_e32 v159, v156
	s_mul_i32 s8, s8, 6
	s_cmp_gt_i32 s10, 31
	s_cselect_b32 s8, s8, 0xc0
	v_lshl_add_u32 v130, v130, 2, s9
	s_ashr_i32 s9, s8, 31
	s_lshl_b64 s[8:9], s[8:9], 12
	v_readlane_b32 s12, v255, 14
	v_readlane_b32 s13, v255, 15
	s_add_u32 s8, s12, s8
	v_ashrrev_i32_e32 v131, 31, v130
	s_addc_u32 s9, s13, s9
	v_lshlrev_b64 v[154:155], 2, v[130:131]
	v_lshl_add_u64 v[130:131], s[8:9], 0, v[154:155]
	s_mov_b64 s[8:9], 0x5000
	v_lshl_add_u64 v[132:133], v[130:131], 0, s[8:9]
	s_movk_i32 s8, 0x5000
	v_add_co_u32_e32 v130, vcc, s8, v130
	s_lshl_b32 s8, s10, 8
	s_add_i32 s8, s8, s44
	v_add_u32_e32 v160, s8, v159
	v_ashrrev_i32_e32 v161, 31, v160
	v_readlane_b32 s8, v254, 0
	v_lshlrev_b64 v[160:161], 12, v[160:161]
	v_readlane_b32 s9, v254, 1
	v_addc_co_u32_e32 v131, vcc, 0, v131, vcc
	s_nop 0
	v_lshl_add_u64 v[160:161], s[8:9], 0, v[160:161]
	v_lshl_add_u64 v[154:155], v[160:161], 0, v[154:155]
	v_add_co_u32_e32 v176, vcc, s45, v154
	global_load_dwordx4 v[138:141], v[132:133], off offset:64
	global_load_dwordx4 v[134:137], v[132:133], off offset:512
	global_load_dwordx4 v[142:145], v[130:131], off
	s_nop 0
	global_load_dwordx4 v[130:133], v[132:133], off offset:576
	v_addc_co_u32_e32 v177, vcc, 0, v155, vcc
	v_add_co_u32_e32 v208, vcc, s19, v154
	global_load_dwordx4 v[160:163], v[154:155], off
	global_load_dwordx4 v[164:167], v[154:155], off offset:64
	global_load_dwordx4 v[168:171], v[154:155], off offset:512
	global_load_dwordx4 v[172:175], v[154:155], off offset:576
	v_addc_co_u32_e32 v209, vcc, 0, v155, vcc
	v_add_co_u32_e32 v246, vcc, s88, v154
	global_load_dwordx4 v[180:183], v[176:177], off
	global_load_dwordx4 v[184:187], v[176:177], off offset:64
	global_load_dwordx4 v[188:191], v[176:177], off offset:512
	global_load_dwordx4 v[192:195], v[176:177], off offset:576
	v_addc_co_u32_e32 v247, vcc, 0, v155, vcc
	global_load_dwordx4 v[196:199], v[208:209], off
	global_load_dwordx4 v[200:203], v[208:209], off offset:64
	global_load_dwordx4 v[204:207], v[208:209], off offset:512
	global_load_dwordx4 v[226:229], v[208:209], off offset:576
	global_load_dwordx4 v[230:233], v[246:247], off
	global_load_dwordx4 v[234:237], v[246:247], off offset:64
	global_load_dwordx4 v[238:241], v[246:247], off offset:512
	global_load_dwordx4 v[242:245], v[246:247], off offset:576
	s_mov_b64 s[8:9], 0x30000
	v_lshl_add_u64 v[248:249], v[154:155], 0, s[84:85]
	v_lshl_add_u64 v[250:251], v[154:155], 0, s[82:83]
	v_lshl_add_u64 v[252:253], v[154:155], 0, s[8:9]
	s_waitcnt vmcnt(0)
;     __device__ __forceinline__ void operator()(const AccT& acc, const Unit& u, int wr, int wc, int fr, int fq) const {
;     ...
;                     for (int n = 0; n < 2; ++n) xo[m][bj][n] = *(const f32x4*)(sbase + (size_t)(ai * 128 + m * 16) * 1024 + bj * 128 + n * 16);
;             __builtin_amdgcn_sched_barrier(0);
; #pragma unroll
;             for (int m = 0; m < 4; ++m) { float* rowp = X + (size_t)(row0 + ai * 128 + m * 16) * 1024 + col0;
; #pragma unroll
;                 for (int bj = 0; bj < 2; ++bj)
; #pragma unroll
;                     for (int n = 0; n < 2; ++n) *(f32x4*)(rowp + bj * 128 + n * 16) = xo[m][bj][n] + gv[bj][n] * acc[ai][bj][m][n]; }
	v_pk_fma_f32 v[108:109], v[108:109], v[132:133], v[174:175]
	v_pk_fma_f32 v[106:107], v[106:107], v[130:131], v[172:173]
	v_pk_fma_f32 v[92:93], v[92:93], v[132:133], v[194:195]
	v_pk_fma_f32 v[90:91], v[90:91], v[130:131], v[192:193]
	v_pk_fma_f32 v[76:77], v[76:77], v[132:133], v[228:229]
	v_pk_fma_f32 v[74:75], v[74:75], v[130:131], v[226:227]
	global_store_dwordx4 v[154:155], v[106:109], off offset:576
	global_store_dwordx4 v[248:249], v[90:93], off offset:576
	global_store_dwordx4 v[250:251], v[74:77], off offset:576
	v_pk_fma_f32 v[108:109], v[120:121], v[144:145], v[182:183]
	v_pk_fma_f32 v[106:107], v[118:119], v[142:143], v[180:181]
	v_pk_fma_f32 v[92:93], v[104:105], v[144:145], v[198:199]
	v_pk_fma_f32 v[90:91], v[102:103], v[142:143], v[196:197]
	v_pk_fma_f32 v[76:77], v[88:89], v[144:145], v[232:233]
	v_pk_fma_f32 v[74:75], v[86:87], v[142:143], v[230:231]
	v_pk_fma_f32 v[128:129], v[128:129], v[144:145], v[162:163]
	v_pk_fma_f32 v[126:127], v[126:127], v[142:143], v[160:161]
	v_pk_fma_f32 v[124:125], v[124:125], v[140:141], v[166:167]
	v_pk_fma_f32 v[122:123], v[122:123], v[138:139], v[164:165]
	v_pk_fma_f32 v[116:117], v[116:117], v[136:137], v[170:171]
	v_pk_fma_f32 v[114:115], v[114:115], v[134:135], v[168:169]
	global_store_dwordx4 v[176:177], v[106:109], off
	v_pk_fma_f32 v[100:101], v[100:101], v[136:137], v[190:191]
	v_pk_fma_f32 v[98:99], v[98:99], v[134:135], v[188:189]
	v_pk_fma_f32 v[108:109], v[112:113], v[140:141], v[186:187]
	v_pk_fma_f32 v[106:107], v[110:111], v[138:139], v[184:185]
	global_store_dwordx4 v[208:209], v[90:93], off
	v_pk_fma_f32 v[84:85], v[84:85], v[136:137], v[206:207]
	v_pk_fma_f32 v[82:83], v[82:83], v[134:135], v[204:205]
	v_pk_fma_f32 v[92:93], v[96:97], v[140:141], v[202:203]
	v_pk_fma_f32 v[90:91], v[94:95], v[138:139], v[200:201]
	global_store_dwordx4 v[246:247], v[74:77], off
	v_pk_fma_f32 v[72:73], v[72:73], v[136:137], v[240:241]
	v_pk_fma_f32 v[70:71], v[70:71], v[134:135], v[238:239]
	v_pk_fma_f32 v[76:77], v[80:81], v[140:141], v[236:237]
	v_pk_fma_f32 v[74:75], v[78:79], v[138:139], v[234:235]
	v_pk_fma_f32 v[68:69], v[68:69], v[132:133], v[244:245]
	v_pk_fma_f32 v[66:67], v[66:67], v[130:131], v[242:243]
	global_store_dwordx4 v[154:155], v[126:129], off
	global_store_dwordx4 v[154:155], v[122:125], off offset:64
	global_store_dwordx4 v[154:155], v[114:117], off offset:512
	global_store_dwordx4 v[248:249], v[106:109], off offset:64
	global_store_dwordx4 v[248:249], v[98:101], off offset:512
	global_store_dwordx4 v[250:251], v[90:93], off offset:64
	global_store_dwordx4 v[250:251], v[82:85], off offset:512
	global_store_dwordx4 v[252:253], v[74:77], off offset:64
	global_store_dwordx4 v[252:253], v[70:73], off offset:512
	global_store_dwordx4 v[252:253], v[66:69], off offset:576
	s_mov_b64 s[8:9], 0x80000
	v_lshl_add_u64 v[160:161], v[154:155], 0, s[8:9]
	s_mov_b32 s8, 0x80000
	v_add_co_u32_e32 v162, vcc, s8, v154
	s_mov_b64 s[8:9], 0x90000
	s_nop 0
	v_addc_co_u32_e32 v163, vcc, 0, v155, vcc
	v_lshl_add_u64 v[164:165], v[154:155], 0, s[8:9]
	s_mov_b32 s8, 0x90000
	v_add_co_u32_e32 v166, vcc, s8, v154
	s_mov_b64 s[8:9], 0xa0000
	s_nop 0
	v_addc_co_u32_e32 v167, vcc, 0, v155, vcc
	v_lshl_add_u64 v[168:169], v[154:155], 0, s[8:9]
	s_mov_b32 s8, 0xa0000
	v_add_co_u32_e32 v170, vcc, s8, v154
	s_mov_b64 s[8:9], 0xb0000
	s_nop 0
	v_addc_co_u32_e32 v171, vcc, 0, v155, vcc
	v_lshl_add_u64 v[172:173], v[154:155], 0, s[8:9]
	s_mov_b32 s8, 0xb0000
	v_add_co_u32_e32 v154, vcc, s8, v154
	global_load_dwordx4 v[66:69], v[162:163], off
	global_load_dwordx4 v[70:73], v[162:163], off offset:64
	global_load_dwordx4 v[74:77], v[162:163], off offset:512
	global_load_dwordx4 v[78:81], v[162:163], off offset:576
	v_addc_co_u32_e32 v155, vcc, 0, v155, vcc
	global_load_dwordx4 v[82:85], v[166:167], off
	global_load_dwordx4 v[86:89], v[166:167], off offset:64
	global_load_dwordx4 v[90:93], v[166:167], off offset:512
	global_load_dwordx4 v[94:97], v[166:167], off offset:576
	global_load_dwordx4 v[98:101], v[170:171], off
	global_load_dwordx4 v[102:105], v[170:171], off offset:64
	global_load_dwordx4 v[106:109], v[170:171], off offset:512
	global_load_dwordx4 v[110:113], v[170:171], off offset:576
	global_load_dwordx4 v[114:117], v[154:155], off
	global_load_dwordx4 v[118:121], v[154:155], off offset:64
	global_load_dwordx4 v[122:125], v[154:155], off offset:512
	global_load_dwordx4 v[126:129], v[154:155], off offset:576
	s_waitcnt vmcnt(0)
; #define PG8_WAIT_V(n) asm volatile("s_waitcnt vmcnt(" #n ")" ::: "memory")
; #define PG8_BAR __builtin_amdgcn_s_barrier()
; template <class Epi>
; __device__ __forceinline__ void gemm_phase(LAS unsigned char* lds, const Gemm g, const Epi& E) {
;     ...
;         if (!has_next) break;
; #pragma unroll
;         for (int a = 0; a < 2; ++a)
; #pragma unroll
;             for (int b = 0; b < 2; ++b)
; #pragma unroll
;                 for (int m = 0; m < 4; ++m)
; #pragma unroll
;                     for (int n = 0; n < 2; ++n) acc[a][b][m][n] = (f32x4){0.f, 0.f, 0.f, 0.f};
;         cur = nxt; cA = nA; cB = nB; ++ui;
;     }
;     PG8_WAIT_V(0);
;     if (wr == 0) PG8_BAR;
;     __device__ __forceinline__ void operator()(const AccT& acc, const Unit& u, int wr, int wc, int fr, int fq) const {
;     ...
;             for (int m = 0; m < 4; ++m) { float* rowp = X + (size_t)(row0 + ai * 128 + m * 16) * 1024 + col0;
; #pragma unroll
;                 for (int bj = 0; bj < 2; ++bj)
; #pragma unroll
;                     for (int n = 0; n < 2; ++n) *(f32x4*)(rowp + bj * 128 + n * 16) = xo[m][bj][n] + gv[bj][n] * acc[ai][bj][m][n]; }
	v_pk_fma_f32 v[44:45], v[44:45], v[132:133], v[80:81]
	v_pk_fma_f32 v[42:43], v[42:43], v[130:131], v[78:79]
	v_pk_fma_f32 v[28:29], v[28:29], v[132:133], v[96:97]
	v_pk_fma_f32 v[26:27], v[26:27], v[130:131], v[94:95]
	v_pk_fma_f32 v[12:13], v[12:13], v[132:133], v[112:113]
	v_pk_fma_f32 v[10:11], v[10:11], v[130:131], v[110:111]
	global_store_dwordx4 v[160:161], v[42:45], off offset:576
	global_store_dwordx4 v[164:165], v[26:29], off offset:576
	global_store_dwordx4 v[168:169], v[10:13], off offset:576
	v_pk_fma_f32 v[44:45], v[56:57], v[144:145], v[84:85]
	v_pk_fma_f32 v[42:43], v[54:55], v[142:143], v[82:83]
	v_pk_fma_f32 v[28:29], v[40:41], v[144:145], v[100:101]
	v_pk_fma_f32 v[26:27], v[38:39], v[142:143], v[98:99]
	v_pk_fma_f32 v[12:13], v[24:25], v[144:145], v[116:117]
	v_pk_fma_f32 v[10:11], v[22:23], v[142:143], v[114:115]
	v_pk_fma_f32 v[64:65], v[64:65], v[144:145], v[68:69]
	v_pk_fma_f32 v[62:63], v[62:63], v[142:143], v[66:67]
	v_pk_fma_f32 v[60:61], v[60:61], v[140:141], v[72:73]
	v_pk_fma_f32 v[58:59], v[58:59], v[138:139], v[70:71]
	v_pk_fma_f32 v[52:53], v[52:53], v[136:137], v[76:77]
	v_pk_fma_f32 v[50:51], v[50:51], v[134:135], v[74:75]
	global_store_dwordx4 v[166:167], v[42:45], off
	v_pk_fma_f32 v[36:37], v[36:37], v[136:137], v[92:93]
	v_pk_fma_f32 v[34:35], v[34:35], v[134:135], v[90:91]
	v_pk_fma_f32 v[44:45], v[48:49], v[140:141], v[88:89]
	v_pk_fma_f32 v[42:43], v[46:47], v[138:139], v[86:87]
	global_store_dwordx4 v[170:171], v[26:29], off
	v_pk_fma_f32 v[20:21], v[20:21], v[136:137], v[108:109]
	v_pk_fma_f32 v[18:19], v[18:19], v[134:135], v[106:107]
	v_pk_fma_f32 v[28:29], v[32:33], v[140:141], v[104:105]
	v_pk_fma_f32 v[26:27], v[30:31], v[138:139], v[102:103]
	global_store_dwordx4 v[154:155], v[10:13], off
	v_pk_fma_f32 v[8:9], v[8:9], v[136:137], v[124:125]
	v_pk_fma_f32 v[6:7], v[6:7], v[134:135], v[122:123]
	v_pk_fma_f32 v[12:13], v[16:17], v[140:141], v[120:121]
	v_pk_fma_f32 v[10:11], v[14:15], v[138:139], v[118:119]
	v_pk_fma_f32 v[4:5], v[4:5], v[132:133], v[128:129]
	v_pk_fma_f32 v[2:3], v[2:3], v[130:131], v[126:127]
	global_store_dwordx4 v[162:163], v[62:65], off
	global_store_dwordx4 v[160:161], v[58:61], off offset:64
	global_store_dwordx4 v[160:161], v[50:53], off offset:512
	global_store_dwordx4 v[164:165], v[42:45], off offset:64
	global_store_dwordx4 v[164:165], v[34:37], off offset:512
	global_store_dwordx4 v[168:169], v[26:29], off offset:64
	global_store_dwordx4 v[168:169], v[18:21], off offset:512
	global_store_dwordx4 v[172:173], v[10:13], off offset:64
	global_store_dwordx4 v[172:173], v[6:9], off offset:512
	global_store_dwordx4 v[172:173], v[2:5], off offset:576
	s_and_b64 vcc, exec, s[2:3]
	s_mov_b32 s61, s59
	s_mov_b32 s64, s60
	s_mov_b64 s[10:11], s[6:7]
	s_mov_b64 s[8:9], s[4:5]
	s_cbranch_vccz .LBB0_540
	s_waitcnt vmcnt(0)
	s_cmpk_gt_u32 s1, 0xff
	s_movk_i32 s36, 0xf000
	s_cbranch_scc1 .LBB0_551
	s_barrier
